# hyena_x batch-pair iteration: the eight row-copy loads issued together (distinct destination registers, counted vmcnt) instead of load / vmcnt(0) / ds_write one at a time
# speedup vs baseline: 1.0215x; 1.0044x over previous
.LBB0_794:
	s_xor_b64 s[40:41], s[2:3], -1
	s_lshl_b32 s2, s42, 1
	s_or_b32 s2, s2, 1
	s_mul_i32 s3, s42, 0x1800
	s_add_u32 s10, s1, s3
	v_mov_b32_e32 v30, v0
	s_addc_u32 s11, s8, 0
	s_lshl_b64 s[10:11], s[10:11], 13
	v_lshlrev_b32_e32 v26, 3, v30
	s_add_u32 s10, s24, s10
	v_ashrrev_i32_e32 v27, 31, v26
	s_addc_u32 s11, s25, s11
	v_lshlrev_b64 v[28:29], 1, v[26:27]
	v_lshl_add_u64 v[22:23], s[10:11], 0, v[28:29]
	global_load_dwordx4 v[194:197], v[22:23], off
	v_lshl_add_u32 v30, v30, 4, s33
	s_mul_i32 s43, s2, 0xc00
	s_mov_b32 s73, 1
	s_mov_b32 s75, 16
	s_mov_b32 s89, 0
	v_add_u32_e32 v22, 0x800, v26
	v_ashrrev_i32_e32 v23, 31, v22
	v_lshlrev_b64 v[26:27], 1, v[22:23]
	v_lshl_add_u64 v[22:23], s[10:11], 0, v[26:27]
	global_load_dwordx4 v[198:201], v[22:23], off
	s_add_u32 s10, s9, s3
	s_addc_u32 s11, s16, 0
	s_lshl_b64 s[10:11], s[10:11], 13
	s_add_u32 s10, s24, s10
	s_addc_u32 s11, s25, s11
	v_lshl_add_u64 v[22:23], s[10:11], 0, v[28:29]
	global_load_dwordx4 v[202:205], v[22:23], off
	v_lshl_add_u64 v[22:23], s[10:11], 0, v[26:27]
	global_load_dwordx4 v[206:209], v[22:23], off
	s_add_u32 s10, s1, s43
	s_addc_u32 s11, s8, 0
	s_lshl_b64 s[10:11], s[10:11], 13
	s_add_u32 s10, s24, s10
	s_addc_u32 s11, s25, s11
	v_lshl_add_u64 v[22:23], s[10:11], 0, v[28:29]
	global_load_dwordx4 v[210:213], v[22:23], off
	v_lshl_add_u64 v[22:23], s[10:11], 0, v[26:27]
	global_load_dwordx4 v[214:217], v[22:23], off
	s_add_u32 s10, s9, s43
	s_addc_u32 s11, s16, 0
	s_lshl_b64 s[10:11], s[10:11], 13
	s_add_u32 s10, s24, s10
	s_addc_u32 s11, s25, s11
	v_lshl_add_u64 v[22:23], s[10:11], 0, v[28:29]
	global_load_dwordx4 v[218:221], v[22:23], off
	v_lshl_add_u64 v[22:23], s[10:11], 0, v[26:27]
	global_load_dwordx4 v[222:225], v[22:23], off
	s_waitcnt vmcnt(7)
	ds_write_b128 v30, v[194:197] offset:34816
	s_waitcnt vmcnt(6)
	ds_write_b128 v30, v[198:201] offset:38912
	s_waitcnt vmcnt(5)
	ds_write_b128 v30, v[202:205] offset:43008
	s_waitcnt vmcnt(4)
	ds_write_b128 v30, v[206:209] offset:47104
	s_waitcnt vmcnt(3)
	ds_write_b128 v30, v[210:213] offset:51200
	s_waitcnt vmcnt(2)
	ds_write_b128 v30, v[214:217] offset:55296
	s_waitcnt vmcnt(1)
	ds_write_b128 v30, v[218:221] offset:59392
	s_waitcnt vmcnt(0)
	ds_write_b128 v30, v[222:225] offset:63488
	s_waitcnt lgkmcnt(0)
	s_barrier
